# v039 + cross unit-end barrier waits only on lgkmcnt (wide stores drain in the background)
# speedup vs baseline: 1.0024x; 1.0024x over previous
; DI float bf2f(unsigned short u) { return __uint_as_float((unsigned)u << 16); }
; DI unsigned f2bf(float f) { unsigned u = __float_as_uint(f); return (u + 0x7fffu + ((u >> 16) & 1u)) >> 16; }
; DI int crow(int i, int hh) { return (i & 3) + 8 * (i >> 2) + 4 * hh; }
; DI void cross_unit(Ctx A_, LAS unsigned char* lds, int kvb, int hc, size_t row0, int nrows, int wave, int lane) {
;     ...
;     if (act) {
;         l += __shfl_xor(l, 32);
;         if (hh == 0) wsf[32 + r] = l;
;         float rl[16];
; #pragma unroll
;         for (int i = 0; i < 16; ++i) rl[i] = 1.0f / wsf[32 + crow(i, hh)];
; #pragma unroll
;         for (int nb = 0; nb < 4; ++nb)
; #pragma unroll
;             for (int i = 0; i < 16; ++i) {
;                 const int q = rg * 32 + crow(i, hh);
;                 if (q < nrows) { const size_t eo = (row0 + q) * PLD + hc * 256 + dvh * 128 + nb * 32 + r; Y_[(row0 + q) * YLD + C_YC + hc * 256 + dvh * 128 + nb * 32 + r] = (bf16)f2bf(o[nb][i] * rl[i] * bf2f(P[eo + C_ZC])); }
;             }
.LBB0_897:
	s_or_b64 exec, exec, s[34:35]
	s_waitcnt vmcnt(0)
	v_and_b32_e32 v206, 63, v0
	v_lshrrev_b32_e32 v207, 5, v206
	v_and_b32_e32 v206, 31, v206
	v_lshlrev_b32_e32 v206, 1, v206
	v_lshl_or_b32 v206, v207, 10, v206
	v_readfirstlane_b32 s98, v0
	s_lshr_b32 s98, s98, 6
	s_lshl_b32 s98, s98, 13
	s_add_i32 s98, s98, 0x10000
	v_add_u32_e32 v206, s98, v206
	s_lshl_b32 s4, s64, 1
	s_add_u32 s34, s49, s4
	v_lshl_or_b32 v4, v174, 2, s44
	s_addc_u32 s35, s50, 0
	s_waitcnt lgkmcnt(0)
	v_lshlrev_b32_e32 v2, 1, v164
	v_lshl_add_u64 v[8:9], s[34:35], 0, v[2:3]
	v_or_b32_e32 v82, s30, v4
	v_mad_u64_u32 v[4:5], s[34:35], v82, s59, v[8:9]
	s_mul_i32 s2, s31, 0x5800
	v_add_u32_e32 v5, s2, v5
	v_add_co_u32_e32 v4, vcc, s60, v4
	v_add_u32_e32 v101, s40, v162
	s_nop 0
	v_addc_co_u32_e32 v5, vcc, 0, v5, vcc
	ds_read_u16 v83, v206 offset:0
	ds_read_u16 v98, v206 offset:64
	ds_read_u16 v99, v206 offset:128
	ds_read_u16 v100, v206 offset:192
	ds_read_b128 v[84:87], v101 offset:128
	ds_read_b128 v[4:7], v101 offset:160
	s_add_u32 s34, s53, s4
	s_addc_u32 s35, s54, 0
	v_lshl_add_u64 v[10:11], s[34:35], 0, v[2:3]
	s_add_u32 s34, s51, s4
	s_waitcnt lgkmcnt(1)
	v_div_scale_f32 v103, s[4:5], v84, v84, 1.0
	v_rcp_f32_e32 v105, v103
	v_or_b32_e32 v102, 1, v82
	v_mad_u64_u32 v[12:13], s[64:65], v102, s59, v[8:9]
	v_mad_u64_u32 v[88:89], s[4:5], v82, s62, v[10:11]
	v_add_u32_e32 v13, s2, v13
	v_add_co_u32_e64 v90, s[4:5], s60, v12
	s_addc_u32 s35, s52, 0
	s_nop 0
	v_addc_co_u32_e64 v91, s[4:5], 0, v13, s[4:5]
	v_lshl_add_u64 v[12:13], s[34:35], 0, v[2:3]
	v_fma_f32 v2, -v103, v105, 1.0
	v_div_scale_f32 v104, vcc, 1.0, v84, 1.0
	v_fmac_f32_e32 v105, v2, v105
	v_mul_f32_e32 v2, v104, v105
	v_fma_f32 v106, -v103, v2, v104
	v_fmac_f32_e32 v2, v106, v105
	v_fma_f32 v103, -v103, v2, v104
	v_div_fmas_f32 v2, v103, v105, v2
	v_div_fixup_f32 v2, v2, v84, 1.0
	v_mul_f32_e32 v18, v18, v2
	v_mul_f32_e32 v34, v34, v2
	v_mul_f32_e32 v50, v50, v2
	v_mul_f32_e32 v2, v66, v2
	s_mul_i32 s30, s31, 0x1800
	v_lshl_add_u64 v[14:15], v[12:13], 0, s[24:25]
	v_lshl_add_u64 v[16:17], v[12:13], 0, s[26:27]
	v_lshl_add_u64 v[12:13], v[12:13], 0, s[28:29]
	v_add_u32_e32 v89, s30, v89
	v_mad_u64_u32 v[92:93], s[4:5], v82, s62, v[14:15]
	v_mad_u64_u32 v[94:95], s[4:5], v82, s62, v[16:17]
	v_mad_u64_u32 v[96:97], s[4:5], v82, s62, v[12:13]
	v_add_u32_e32 v93, s30, v93
	v_add_u32_e32 v95, s30, v95
	v_add_u32_e32 v97, s30, v97
	s_waitcnt lgkmcnt(0)
	v_lshlrev_b32_e32 v66, 16, v83
	s_waitcnt lgkmcnt(0)
	v_lshlrev_b32_e32 v83, 16, v98
	s_waitcnt lgkmcnt(0)
	v_lshlrev_b32_e32 v84, 16, v99
	s_waitcnt lgkmcnt(0)
	v_lshlrev_b32_e32 v98, 16, v100
	v_mul_f32_e32 v18, v18, v66
	v_mul_f32_e32 v34, v34, v83
	v_mul_f32_e32 v50, v50, v84
	v_mul_f32_e32 v2, v2, v98
	v_bfe_u32 v66, v18, 16, 1
	v_bfe_u32 v83, v34, 16, 1
	v_bfe_u32 v84, v50, 16, 1
	v_bfe_u32 v98, v2, 16, 1
	v_add3_u32 v18, v18, v66, s61
	v_add3_u32 v34, v34, v83, s61
	v_add3_u32 v50, v50, v84, s61
	v_add3_u32 v2, v2, v98, s61
	ds_write_b16_d16_hi v206, v18 offset:0
	ds_write_b16_d16_hi v206, v34 offset:64
	ds_write_b16_d16_hi v206, v50 offset:128
	ds_write_b16_d16_hi v206, v2 offset:192
	ds_read_u16 v2, v206 offset:256
	s_nop 0
	ds_read_u16 v18, v206 offset:320
	ds_read_u16 v34, v206 offset:384
	ds_read_u16 v50, v206 offset:448
	v_or_b32_e32 v83, 2, v82
	v_mad_u64_u32 v[88:89], s[4:5], v83, s59, v[8:9]
	v_div_scale_f32 v84, s[4:5], v85, v85, 1.0
	v_mad_u64_u32 v[90:91], s[4:5], v102, s62, v[10:11]
	v_add_u32_e32 v66, s2, v89
	v_add_co_u32_e64 v88, s[4:5], s60, v88
	v_div_scale_f32 v98, vcc, 1.0, v85, 1.0
	s_nop 0
	v_addc_co_u32_e64 v89, s[4:5], 0, v66, s[4:5]
	v_rcp_f32_e32 v66, v84
	v_add_u32_e32 v91, s30, v91
	v_mad_u64_u32 v[92:93], s[4:5], v102, s62, v[14:15]
	v_fma_f32 v99, -v84, v66, 1.0
	v_fmac_f32_e32 v66, v99, v66
	v_mul_f32_e32 v99, v98, v66
	v_fma_f32 v100, -v84, v99, v98
	v_fmac_f32_e32 v99, v100, v66
	v_fma_f32 v84, -v84, v99, v98
	v_div_fmas_f32 v66, v84, v66, v99
	v_div_fixup_f32 v66, v66, v85, 1.0
	v_mul_f32_e32 v19, v19, v66
	v_mul_f32_e32 v35, v35, v66
	v_mul_f32_e32 v51, v51, v66
	v_mul_f32_e32 v66, v67, v66
	v_mad_u64_u32 v[94:95], s[4:5], v102, s62, v[16:17]
	v_mad_u64_u32 v[96:97], s[4:5], v102, s62, v[12:13]
	v_add_u32_e32 v93, s30, v93
	v_add_u32_e32 v95, s30, v95
	v_add_u32_e32 v97, s30, v97
	s_waitcnt lgkmcnt(0)
	v_lshlrev_b32_e32 v2, 16, v2
	s_waitcnt lgkmcnt(0)
	v_lshlrev_b32_e32 v18, 16, v18
	s_waitcnt lgkmcnt(0)
	v_lshlrev_b32_e32 v34, 16, v34
	s_waitcnt lgkmcnt(0)
	v_lshlrev_b32_e32 v50, 16, v50
	v_mul_f32_e32 v2, v19, v2
	v_mul_f32_e32 v18, v35, v18
	v_mul_f32_e32 v19, v51, v34
	v_mul_f32_e32 v34, v66, v50
	v_bfe_u32 v35, v2, 16, 1
	v_bfe_u32 v50, v18, 16, 1
	v_bfe_u32 v51, v19, 16, 1
	v_bfe_u32 v66, v34, 16, 1
	v_add3_u32 v2, v2, v35, s61
	v_add3_u32 v18, v18, v50, s61
	v_add3_u32 v19, v19, v51, s61
	v_add3_u32 v34, v34, v66, s61
	ds_write_b16_d16_hi v206, v2 offset:256
	ds_write_b16_d16_hi v206, v18 offset:320
	ds_write_b16_d16_hi v206, v19 offset:384
	ds_write_b16_d16_hi v206, v34 offset:448
	ds_read_u16 v2, v206 offset:512
	s_nop 0
	ds_read_u16 v90, v206 offset:576
	ds_read_u16 v91, v206 offset:640
	s_nop 0
	ds_read_u16 v88, v206 offset:704
	v_div_scale_f32 v92, s[4:5], v86, v86, 1.0
	v_rcp_f32_e32 v94, v92
	v_or_b32_e32 v89, 3, v82
	v_mad_u64_u32 v[18:19], s[4:5], v89, s59, v[8:9]
	v_mad_u64_u32 v[34:35], s[4:5], v83, s62, v[10:11]
	v_add_u32_e32 v19, s2, v19
	v_add_co_u32_e64 v18, s[4:5], s60, v18
	v_div_scale_f32 v93, vcc, 1.0, v86, 1.0
	s_nop 0
	v_addc_co_u32_e64 v19, s[4:5], 0, v19, s[4:5]
	v_mad_u64_u32 v[50:51], s[4:5], v83, s62, v[14:15]
	v_mad_u64_u32 v[66:67], s[4:5], v83, s62, v[16:17]
	v_mad_u64_u32 v[84:85], s[4:5], v83, s62, v[12:13]
	v_fma_f32 v83, -v92, v94, 1.0
	v_fmac_f32_e32 v94, v83, v94
	v_mul_f32_e32 v83, v93, v94
	v_fma_f32 v95, -v92, v83, v93
	v_fmac_f32_e32 v83, v95, v94
	v_fma_f32 v92, -v92, v83, v93
	v_div_fmas_f32 v83, v92, v94, v83
	v_div_fixup_f32 v83, v83, v86, 1.0
	v_mul_f32_e32 v20, v20, v83
	v_mul_f32_e32 v36, v36, v83
	v_mul_f32_e32 v52, v52, v83
	v_mul_f32_e32 v68, v68, v83
	v_add_u32_e32 v35, s30, v35
	v_add_u32_e32 v51, s30, v51
	v_add_u32_e32 v67, s30, v67
	v_add_u32_e32 v85, s30, v85
	s_waitcnt lgkmcnt(0)
; DI float bf2f(unsigned short u) { return __uint_as_float((unsigned)u << 16); }
; DI unsigned f2bf(float f) { unsigned u = __float_as_uint(f); return (u + 0x7fffu + ((u >> 16) & 1u)) >> 16; }
; DI int crow(int i, int hh) { return (i & 3) + 8 * (i >> 2) + 4 * hh; }
; DI void cross_unit(Ctx A_, LAS unsigned char* lds, int kvb, int hc, size_t row0, int nrows, int wave, int lane) {
;     ...
; #pragma unroll
;         for (int nb = 0; nb < 4; ++nb)
; #pragma unroll
;             for (int i = 0; i < 16; ++i) {
;                 const int q = rg * 32 + crow(i, hh);
;                 if (q < nrows) { const size_t eo = (row0 + q) * PLD + hc * 256 + dvh * 128 + nb * 32 + r; Y_[(row0 + q) * YLD + C_YC + hc * 256 + dvh * 128 + nb * 32 + r] = (bf16)f2bf(o[nb][i] * rl[i] * bf2f(P[eo + C_ZC])); }
;             }
	v_lshlrev_b32_e32 v2, 16, v2
	s_waitcnt lgkmcnt(0)
	v_lshlrev_b32_e32 v83, 16, v90
	s_waitcnt lgkmcnt(0)
	v_lshlrev_b32_e32 v86, 16, v91
	s_waitcnt lgkmcnt(0)
	v_lshlrev_b32_e32 v88, 16, v88
	v_mul_f32_e32 v2, v20, v2
	v_mul_f32_e32 v20, v36, v83
	v_mul_f32_e32 v36, v52, v86
	v_mul_f32_e32 v52, v68, v88
	v_bfe_u32 v68, v2, 16, 1
	v_bfe_u32 v83, v20, 16, 1
	v_bfe_u32 v86, v36, 16, 1
	v_bfe_u32 v88, v52, 16, 1
	v_add3_u32 v2, v2, v68, s61
	v_add3_u32 v20, v20, v83, s61
	v_add3_u32 v36, v36, v86, s61
	v_add3_u32 v52, v52, v88, s61
	ds_write_b16_d16_hi v206, v2 offset:512
	ds_write_b16_d16_hi v206, v20 offset:576
	ds_write_b16_d16_hi v206, v36 offset:640
	ds_write_b16_d16_hi v206, v52 offset:704
	ds_read_u16 v2, v206 offset:768
	s_nop 0
	ds_read_u16 v20, v206 offset:832
	ds_read_u16 v36, v206 offset:896
	ds_read_u16 v52, v206 offset:960
	v_div_scale_f32 v83, s[4:5], v87, v87, 1.0
	v_rcp_f32_e32 v88, v83
	v_or_b32_e32 v68, 8, v82
	v_mad_u64_u32 v[18:19], s[4:5], v68, s59, v[8:9]
	v_mad_u64_u32 v[34:35], s[4:5], v89, s62, v[10:11]
	v_add_u32_e32 v19, s2, v19
	v_add_co_u32_e64 v18, s[4:5], s60, v18
	v_div_scale_f32 v86, vcc, 1.0, v87, 1.0
	s_nop 0
	v_addc_co_u32_e64 v19, s[4:5], 0, v19, s[4:5]
	v_mad_u64_u32 v[50:51], s[4:5], v89, s62, v[14:15]
	v_mad_u64_u32 v[66:67], s[4:5], v89, s62, v[16:17]
	v_mad_u64_u32 v[84:85], s[4:5], v89, s62, v[12:13]
	v_fma_f32 v89, -v83, v88, 1.0
	v_fmac_f32_e32 v88, v89, v88
	v_mul_f32_e32 v89, v86, v88
	v_fma_f32 v90, -v83, v89, v86
	v_fmac_f32_e32 v89, v90, v88
	v_fma_f32 v83, -v83, v89, v86
	v_div_fmas_f32 v83, v83, v88, v89
	v_div_fixup_f32 v83, v83, v87, 1.0
	v_mul_f32_e32 v21, v21, v83
	v_mul_f32_e32 v37, v37, v83
	v_mul_f32_e32 v53, v53, v83
	v_mul_f32_e32 v69, v69, v83
	v_add_u32_e32 v35, s30, v35
	v_add_u32_e32 v51, s30, v51
	v_add_u32_e32 v67, s30, v67
	v_add_u32_e32 v85, s30, v85
	s_waitcnt lgkmcnt(0)
	v_div_scale_f32 v83, vcc, 1.0, v4, 1.0
	s_waitcnt lgkmcnt(0)
	v_lshlrev_b32_e32 v2, 16, v2
	s_waitcnt lgkmcnt(0)
	v_lshlrev_b32_e32 v20, 16, v20
	s_waitcnt lgkmcnt(0)
	v_lshlrev_b32_e32 v36, 16, v36
	s_waitcnt lgkmcnt(0)
	v_lshlrev_b32_e32 v52, 16, v52
	v_mul_f32_e32 v2, v21, v2
	v_mul_f32_e32 v20, v37, v20
	v_mul_f32_e32 v21, v53, v36
	v_mul_f32_e32 v36, v69, v52
	v_bfe_u32 v37, v2, 16, 1
	v_bfe_u32 v52, v20, 16, 1
	v_bfe_u32 v53, v21, 16, 1
	v_bfe_u32 v69, v36, 16, 1
	v_add3_u32 v2, v2, v37, s61
	v_add3_u32 v20, v20, v52, s61
	v_add3_u32 v21, v21, v53, s61
	v_add3_u32 v36, v36, v69, s61
	ds_write_b16_d16_hi v206, v2 offset:768
	ds_write_b16_d16_hi v206, v20 offset:832
	ds_write_b16_d16_hi v206, v21 offset:896
	ds_write_b16_d16_hi v206, v36 offset:960
	ds_read_u16 v2, v206 offset:2048
	s_nop 0
	ds_read_u16 v52, v206 offset:2112
	ds_read_u16 v53, v206 offset:2176
	ds_read_u16 v66, v206 offset:2240
	v_div_scale_f32 v69, s[4:5], v4, v4, 1.0
	v_rcp_f32_e32 v84, v69
	v_or_b32_e32 v67, 9, v82
	v_mad_u64_u32 v[18:19], s[4:5], v67, s59, v[8:9]
	v_mad_u64_u32 v[20:21], s[4:5], v68, s62, v[10:11]
	v_add_u32_e32 v19, s2, v19
	v_add_co_u32_e64 v18, s[4:5], s60, v18
	v_add_u32_e32 v21, s30, v21
	s_nop 0
	v_addc_co_u32_e64 v19, s[4:5], 0, v19, s[4:5]
	v_mad_u64_u32 v[34:35], s[4:5], v68, s62, v[14:15]
	v_mad_u64_u32 v[36:37], s[4:5], v68, s62, v[16:17]
	v_mad_u64_u32 v[50:51], s[4:5], v68, s62, v[12:13]
	v_fma_f32 v68, -v69, v84, 1.0
	v_fmac_f32_e32 v84, v68, v84
	v_mul_f32_e32 v68, v83, v84
	v_fma_f32 v85, -v69, v68, v83
	v_fmac_f32_e32 v68, v85, v84
	v_fma_f32 v69, -v69, v68, v83
	v_div_fmas_f32 v68, v69, v84, v68
	v_div_fixup_f32 v4, v68, v4, 1.0
	v_mul_f32_e32 v22, v22, v4
	v_mul_f32_e32 v38, v38, v4
	v_mul_f32_e32 v54, v54, v4
	v_mul_f32_e32 v4, v70, v4
	v_add_u32_e32 v35, s30, v35
	v_add_u32_e32 v37, s30, v37
	v_add_u32_e32 v51, s30, v51
	s_waitcnt lgkmcnt(0)
	v_lshlrev_b32_e32 v2, 16, v2
	s_waitcnt lgkmcnt(0)
	v_lshlrev_b32_e32 v52, 16, v52
	s_waitcnt lgkmcnt(0)
	v_lshlrev_b32_e32 v53, 16, v53
	s_waitcnt lgkmcnt(0)
	v_lshlrev_b32_e32 v66, 16, v66
	v_mul_f32_e32 v2, v22, v2
	v_mul_f32_e32 v22, v38, v52
	v_mul_f32_e32 v38, v54, v53
	v_mul_f32_e32 v4, v4, v66
	v_bfe_u32 v52, v2, 16, 1
	v_bfe_u32 v53, v22, 16, 1
	v_bfe_u32 v54, v38, 16, 1
	v_bfe_u32 v66, v4, 16, 1
	v_add3_u32 v2, v2, v52, s61
	v_add3_u32 v22, v22, v53, s61
	v_add3_u32 v38, v38, v54, s61
	v_add3_u32 v4, v4, v66, s61
	ds_write_b16_d16_hi v206, v2 offset:2048
	ds_write_b16_d16_hi v206, v22 offset:2112
	ds_write_b16_d16_hi v206, v38 offset:2176
	ds_write_b16_d16_hi v206, v4 offset:2240
	ds_read_u16 v2, v206 offset:2304
	s_nop 0
	ds_read_u16 v4, v206 offset:2368
	ds_read_u16 v22, v206 offset:2432
	ds_read_u16 v38, v206 offset:2496
	v_div_scale_f32 v53, s[4:5], v5, v5, 1.0
	v_rcp_f32_e32 v66, v53
	v_or_b32_e32 v52, 10, v82
	v_mad_u64_u32 v[18:19], s[4:5], v52, s59, v[8:9]
	v_mad_u64_u32 v[20:21], s[4:5], v67, s62, v[10:11]
	v_add_u32_e32 v19, s2, v19
	v_add_co_u32_e64 v18, s[4:5], s60, v18
	v_div_scale_f32 v54, vcc, 1.0, v5, 1.0
	s_nop 0
	v_addc_co_u32_e64 v19, s[4:5], 0, v19, s[4:5]
	v_mad_u64_u32 v[34:35], s[4:5], v67, s62, v[14:15]
	v_mad_u64_u32 v[36:37], s[4:5], v67, s62, v[16:17]
	v_mad_u64_u32 v[50:51], s[4:5], v67, s62, v[12:13]
	v_fma_f32 v67, -v53, v66, 1.0
	v_fmac_f32_e32 v66, v67, v66
	v_mul_f32_e32 v67, v54, v66
	v_fma_f32 v68, -v53, v67, v54
	v_fmac_f32_e32 v67, v68, v66
	v_fma_f32 v53, -v53, v67, v54
	v_div_fmas_f32 v53, v53, v66, v67
	v_div_fixup_f32 v5, v53, v5, 1.0
	v_mul_f32_e32 v23, v23, v5
	v_mul_f32_e32 v39, v39, v5
	v_mul_f32_e32 v53, v55, v5
	v_mul_f32_e32 v5, v71, v5
	v_add_u32_e32 v21, s30, v21
	v_add_u32_e32 v35, s30, v35
	v_add_u32_e32 v37, s30, v37
	v_add_u32_e32 v51, s30, v51
	s_waitcnt lgkmcnt(0)
; DI float bf2f(unsigned short u) { return __uint_as_float((unsigned)u << 16); }
; DI unsigned f2bf(float f) { unsigned u = __float_as_uint(f); return (u + 0x7fffu + ((u >> 16) & 1u)) >> 16; }
; DI int crow(int i, int hh) { return (i & 3) + 8 * (i >> 2) + 4 * hh; }
; DI void cross_unit(Ctx A_, LAS unsigned char* lds, int kvb, int hc, size_t row0, int nrows, int wave, int lane) {
;     ...
; #pragma unroll
;         for (int nb = 0; nb < 4; ++nb)
; #pragma unroll
;             for (int i = 0; i < 16; ++i) {
;                 const int q = rg * 32 + crow(i, hh);
;                 if (q < nrows) { const size_t eo = (row0 + q) * PLD + hc * 256 + dvh * 128 + nb * 32 + r; Y_[(row0 + q) * YLD + C_YC + hc * 256 + dvh * 128 + nb * 32 + r] = (bf16)f2bf(o[nb][i] * rl[i] * bf2f(P[eo + C_ZC])); }
;             }
	v_lshlrev_b32_e32 v2, 16, v2
	s_waitcnt lgkmcnt(0)
	v_lshlrev_b32_e32 v4, 16, v4
	s_waitcnt lgkmcnt(0)
	v_lshlrev_b32_e32 v22, 16, v22
	s_waitcnt lgkmcnt(0)
	v_lshlrev_b32_e32 v38, 16, v38
	v_mul_f32_e32 v2, v23, v2
	v_mul_f32_e32 v4, v39, v4
	v_mul_f32_e32 v22, v53, v22
	v_mul_f32_e32 v5, v5, v38
	v_bfe_u32 v23, v2, 16, 1
	v_bfe_u32 v38, v4, 16, 1
	v_bfe_u32 v39, v22, 16, 1
	v_bfe_u32 v53, v5, 16, 1
	v_add3_u32 v2, v2, v23, s61
	v_add3_u32 v4, v4, v38, s61
	v_add3_u32 v22, v22, v39, s61
	v_add3_u32 v5, v5, v53, s61
	ds_write_b16_d16_hi v206, v2 offset:2304
	ds_write_b16_d16_hi v206, v4 offset:2368
	ds_write_b16_d16_hi v206, v22 offset:2432
	ds_write_b16_d16_hi v206, v5 offset:2496
	ds_read_u16 v2, v206 offset:2560
	s_nop 0
	ds_read_u16 v36, v206 offset:2624
	ds_read_u16 v37, v206 offset:2688
	ds_read_u16 v38, v206 offset:2752
	v_div_scale_f32 v50, s[4:5], v6, v6, 1.0
	v_rcp_f32_e32 v53, v50
	v_or_b32_e32 v39, 11, v82
	v_mad_u64_u32 v[4:5], s[4:5], v39, s59, v[8:9]
	v_mad_u64_u32 v[18:19], s[4:5], v52, s62, v[10:11]
	v_add_u32_e32 v5, s2, v5
	v_add_co_u32_e64 v4, s[4:5], s60, v4
	v_div_scale_f32 v51, vcc, 1.0, v6, 1.0
	s_nop 0
	v_addc_co_u32_e64 v5, s[4:5], 0, v5, s[4:5]
	v_mad_u64_u32 v[20:21], s[4:5], v52, s62, v[14:15]
	v_mad_u64_u32 v[22:23], s[4:5], v52, s62, v[16:17]
	v_mad_u64_u32 v[34:35], s[4:5], v52, s62, v[12:13]
	v_fma_f32 v52, -v50, v53, 1.0
	v_fmac_f32_e32 v53, v52, v53
	v_mul_f32_e32 v52, v51, v53
	v_fma_f32 v54, -v50, v52, v51
	v_fmac_f32_e32 v52, v54, v53
	v_fma_f32 v50, -v50, v52, v51
	v_div_fmas_f32 v50, v50, v53, v52
	v_div_fixup_f32 v6, v50, v6, 1.0
	v_mul_f32_e32 v24, v24, v6
	v_mul_f32_e32 v40, v40, v6
	v_mul_f32_e32 v50, v56, v6
	v_mul_f32_e32 v6, v72, v6
	v_add_u32_e32 v19, s30, v19
	v_add_u32_e32 v21, s30, v21
	v_add_u32_e32 v23, s30, v23
	v_add_u32_e32 v35, s30, v35
	s_waitcnt lgkmcnt(0)
	v_lshlrev_b32_e32 v2, 16, v2
	s_waitcnt lgkmcnt(0)
	v_lshlrev_b32_e32 v36, 16, v36
	s_waitcnt lgkmcnt(0)
	v_lshlrev_b32_e32 v37, 16, v37
	s_waitcnt lgkmcnt(0)
	v_lshlrev_b32_e32 v38, 16, v38
	v_mul_f32_e32 v2, v24, v2
	v_mul_f32_e32 v24, v40, v36
	v_mul_f32_e32 v36, v50, v37
	v_mul_f32_e32 v6, v6, v38
	v_bfe_u32 v37, v2, 16, 1
	v_bfe_u32 v38, v24, 16, 1
	v_bfe_u32 v40, v36, 16, 1
	v_bfe_u32 v50, v6, 16, 1
	v_add3_u32 v2, v2, v37, s61
	v_add3_u32 v24, v24, v38, s61
	v_add3_u32 v36, v36, v40, s61
	v_add3_u32 v6, v6, v50, s61
	ds_write_b16_d16_hi v206, v2 offset:2560
	ds_write_b16_d16_hi v206, v24 offset:2624
	ds_write_b16_d16_hi v206, v36 offset:2688
	ds_write_b16_d16_hi v206, v6 offset:2752
	ds_read_u16 v2, v206 offset:2816
	s_nop 0
	ds_read_u16 v6, v206 offset:2880
	ds_read_u16 v24, v206 offset:2944
	ds_read_u16 v36, v206 offset:3008
	v_div_scale_f32 v37, s[4:5], v7, v7, 1.0
	v_rcp_f32_e32 v50, v37
	v_or_b32_e32 v38, 16, v82
	v_mad_u64_u32 v[4:5], s[4:5], v38, s59, v[8:9]
	v_mad_u64_u32 v[18:19], s[4:5], v39, s62, v[10:11]
	v_add_u32_e32 v5, s2, v5
	v_add_co_u32_e64 v4, s[4:5], s60, v4
	v_div_scale_f32 v40, vcc, 1.0, v7, 1.0
	s_nop 0
	v_addc_co_u32_e64 v5, s[4:5], 0, v5, s[4:5]
	v_mad_u64_u32 v[20:21], s[4:5], v39, s62, v[14:15]
	v_mad_u64_u32 v[22:23], s[4:5], v39, s62, v[16:17]
	v_mad_u64_u32 v[34:35], s[4:5], v39, s62, v[12:13]
	v_fma_f32 v39, -v37, v50, 1.0
	v_fmac_f32_e32 v50, v39, v50
	v_mul_f32_e32 v39, v40, v50
	v_fma_f32 v51, -v37, v39, v40
	v_fmac_f32_e32 v39, v51, v50
	v_fma_f32 v37, -v37, v39, v40
	v_div_fmas_f32 v37, v37, v50, v39
	v_div_fixup_f32 v7, v37, v7, 1.0
	v_mul_f32_e32 v25, v25, v7
	v_mul_f32_e32 v37, v41, v7
	v_mul_f32_e32 v39, v57, v7
	v_mul_f32_e32 v7, v73, v7
	v_add_u32_e32 v19, s30, v19
	v_add_u32_e32 v21, s30, v21
	v_add_u32_e32 v23, s30, v23
	v_add_u32_e32 v35, s30, v35
	v_or_b32_e32 v51, 17, v82
	s_waitcnt lgkmcnt(0)
	v_lshlrev_b32_e32 v2, 16, v2
	s_waitcnt lgkmcnt(0)
	v_lshlrev_b32_e32 v6, 16, v6
	s_waitcnt lgkmcnt(0)
	v_lshlrev_b32_e32 v24, 16, v24
	s_waitcnt lgkmcnt(0)
	v_lshlrev_b32_e32 v36, 16, v36
	v_mul_f32_e32 v2, v25, v2
	v_mul_f32_e32 v6, v37, v6
	v_mul_f32_e32 v24, v39, v24
	v_mul_f32_e32 v7, v7, v36
	v_bfe_u32 v25, v2, 16, 1
	v_bfe_u32 v36, v6, 16, 1
	v_bfe_u32 v37, v24, 16, 1
	v_bfe_u32 v39, v7, 16, 1
	v_add3_u32 v2, v2, v25, s61
	v_add3_u32 v6, v6, v36, s61
	v_add3_u32 v24, v24, v37, s61
	v_add3_u32 v7, v7, v39, s61
	ds_write_b16_d16_hi v206, v2 offset:2816
	ds_write_b16_d16_hi v206, v6 offset:2880
	ds_write_b16_d16_hi v206, v24 offset:2944
	ds_write_b16_d16_hi v206, v7 offset:3008
	ds_read_u16 v2, v206 offset:4096
	s_nop 0
	ds_read_u16 v40, v206 offset:4160
	ds_read_u16 v41, v206 offset:4224
	ds_read_u16 v50, v206 offset:4288
	ds_read_b128 v[18:21], v101 offset:192
	ds_read_b128 v[4:7], v101 offset:224
	v_mad_u64_u32 v[22:23], s[4:5], v51, s59, v[8:9]
	v_mad_u64_u32 v[24:25], s[4:5], v38, s62, v[10:11]
	s_waitcnt lgkmcnt(1)
	v_div_scale_f32 v52, s[4:5], v18, v18, 1.0
	v_rcp_f32_e32 v54, v52
	v_div_scale_f32 v53, vcc, 1.0, v18, 1.0
	v_add_u32_e32 v23, s2, v23
	v_fma_f32 v55, -v52, v54, 1.0
	v_fmac_f32_e32 v54, v55, v54
	v_mul_f32_e32 v55, v53, v54
	v_fma_f32 v56, -v52, v55, v53
	v_fmac_f32_e32 v55, v56, v54
	v_fma_f32 v52, -v52, v55, v53
	v_div_fmas_f32 v52, v52, v54, v55
	v_div_fixup_f32 v18, v52, v18, 1.0
	v_mul_f32_e32 v26, v26, v18
	v_mul_f32_e32 v42, v42, v18
	v_mul_f32_e32 v52, v58, v18
	v_mul_f32_e32 v18, v74, v18
	v_add_co_u32_e64 v22, s[4:5], s60, v22
	v_add_u32_e32 v25, s30, v25
	s_nop 0
	v_addc_co_u32_e64 v23, s[4:5], 0, v23, s[4:5]
	v_mad_u64_u32 v[34:35], s[4:5], v38, s62, v[14:15]
	v_mad_u64_u32 v[36:37], s[4:5], v38, s62, v[16:17]
	v_mad_u64_u32 v[38:39], s[4:5], v38, s62, v[12:13]
	v_add_u32_e32 v35, s30, v35
	v_add_u32_e32 v37, s30, v37
	v_add_u32_e32 v39, s30, v39
	s_waitcnt lgkmcnt(0)
; DI float bf2f(unsigned short u) { return __uint_as_float((unsigned)u << 16); }
; DI unsigned f2bf(float f) { unsigned u = __float_as_uint(f); return (u + 0x7fffu + ((u >> 16) & 1u)) >> 16; }
; DI int crow(int i, int hh) { return (i & 3) + 8 * (i >> 2) + 4 * hh; }
; DI void cross_unit(Ctx A_, LAS unsigned char* lds, int kvb, int hc, size_t row0, int nrows, int wave, int lane) {
;     ...
; #pragma unroll
;         for (int nb = 0; nb < 4; ++nb)
; #pragma unroll
;             for (int i = 0; i < 16; ++i) {
;                 const int q = rg * 32 + crow(i, hh);
;                 if (q < nrows) { const size_t eo = (row0 + q) * PLD + hc * 256 + dvh * 128 + nb * 32 + r; Y_[(row0 + q) * YLD + C_YC + hc * 256 + dvh * 128 + nb * 32 + r] = (bf16)f2bf(o[nb][i] * rl[i] * bf2f(P[eo + C_ZC])); }
;             }
	v_lshlrev_b32_e32 v2, 16, v2
	s_waitcnt lgkmcnt(0)
	v_lshlrev_b32_e32 v40, 16, v40
	s_waitcnt lgkmcnt(0)
	v_lshlrev_b32_e32 v41, 16, v41
	s_waitcnt lgkmcnt(0)
	v_lshlrev_b32_e32 v50, 16, v50
	v_mul_f32_e32 v2, v26, v2
	v_mul_f32_e32 v26, v42, v40
	v_mul_f32_e32 v40, v52, v41
	v_mul_f32_e32 v18, v18, v50
	v_bfe_u32 v41, v2, 16, 1
	v_bfe_u32 v42, v26, 16, 1
	v_bfe_u32 v50, v40, 16, 1
	v_bfe_u32 v52, v18, 16, 1
	v_add3_u32 v2, v2, v41, s61
	v_add3_u32 v26, v26, v42, s61
	v_add3_u32 v40, v40, v50, s61
	v_add3_u32 v18, v18, v52, s61
	ds_write_b16_d16_hi v206, v2 offset:4096
	ds_write_b16_d16_hi v206, v26 offset:4160
	ds_write_b16_d16_hi v206, v40 offset:4224
	ds_write_b16_d16_hi v206, v18 offset:4288
	ds_read_u16 v2, v206 offset:4352
	s_nop 0
	ds_read_u16 v18, v206 offset:4416
	ds_read_u16 v26, v206 offset:4480
	ds_read_u16 v40, v206 offset:4544
	v_div_scale_f32 v42, s[4:5], v19, v19, 1.0
	v_rcp_f32_e32 v52, v42
	v_or_b32_e32 v41, 18, v82
	v_mad_u64_u32 v[22:23], s[4:5], v41, s59, v[8:9]
	v_mad_u64_u32 v[24:25], s[4:5], v51, s62, v[10:11]
	v_add_u32_e32 v23, s2, v23
	v_add_co_u32_e64 v22, s[4:5], s60, v22
	v_div_scale_f32 v50, vcc, 1.0, v19, 1.0
	s_nop 0
	v_addc_co_u32_e64 v23, s[4:5], 0, v23, s[4:5]
	v_mad_u64_u32 v[34:35], s[4:5], v51, s62, v[14:15]
	v_mad_u64_u32 v[36:37], s[4:5], v51, s62, v[16:17]
	v_mad_u64_u32 v[38:39], s[4:5], v51, s62, v[12:13]
	v_fma_f32 v51, -v42, v52, 1.0
	v_fmac_f32_e32 v52, v51, v52
	v_mul_f32_e32 v51, v50, v52
	v_fma_f32 v53, -v42, v51, v50
	v_fmac_f32_e32 v51, v53, v52
	v_fma_f32 v42, -v42, v51, v50
	v_div_fmas_f32 v42, v42, v52, v51
	v_div_fixup_f32 v19, v42, v19, 1.0
	v_mul_f32_e32 v27, v27, v19
	v_mul_f32_e32 v42, v43, v19
	v_mul_f32_e32 v43, v59, v19
	v_mul_f32_e32 v19, v75, v19
	v_add_u32_e32 v25, s30, v25
	v_add_u32_e32 v35, s30, v35
	v_add_u32_e32 v37, s30, v37
	v_add_u32_e32 v39, s30, v39
	s_waitcnt lgkmcnt(0)
	v_lshlrev_b32_e32 v2, 16, v2
	s_waitcnt lgkmcnt(0)
	v_lshlrev_b32_e32 v18, 16, v18
	s_waitcnt lgkmcnt(0)
	v_lshlrev_b32_e32 v26, 16, v26
	s_waitcnt lgkmcnt(0)
	v_lshlrev_b32_e32 v40, 16, v40
	v_mul_f32_e32 v2, v27, v2
	v_mul_f32_e32 v18, v42, v18
	v_mul_f32_e32 v26, v43, v26
	v_mul_f32_e32 v19, v19, v40
	v_bfe_u32 v27, v2, 16, 1
	v_bfe_u32 v40, v18, 16, 1
	v_bfe_u32 v42, v26, 16, 1
	v_bfe_u32 v43, v19, 16, 1
	v_add3_u32 v2, v2, v27, s61
	v_add3_u32 v18, v18, v40, s61
	v_add3_u32 v26, v26, v42, s61
	v_add3_u32 v19, v19, v43, s61
	ds_write_b16_d16_hi v206, v2 offset:4352
	ds_write_b16_d16_hi v206, v18 offset:4416
	ds_write_b16_d16_hi v206, v26 offset:4480
	ds_write_b16_d16_hi v206, v19 offset:4544
	ds_read_u16 v2, v206 offset:4608
	s_nop 0
	ds_read_u16 v36, v206 offset:4672
	ds_read_u16 v37, v206 offset:4736
	ds_read_u16 v38, v206 offset:4800
	v_div_scale_f32 v40, s[4:5], v20, v20, 1.0
	v_rcp_f32_e32 v43, v40
	v_or_b32_e32 v39, 19, v82
	v_mad_u64_u32 v[18:19], s[4:5], v39, s59, v[8:9]
	v_mad_u64_u32 v[22:23], s[4:5], v41, s62, v[10:11]
	v_add_u32_e32 v19, s2, v19
	v_add_co_u32_e64 v18, s[4:5], s60, v18
	v_div_scale_f32 v42, vcc, 1.0, v20, 1.0
	s_nop 0
	v_addc_co_u32_e64 v19, s[4:5], 0, v19, s[4:5]
	v_mad_u64_u32 v[24:25], s[4:5], v41, s62, v[14:15]
	v_mad_u64_u32 v[26:27], s[4:5], v41, s62, v[16:17]
	v_mad_u64_u32 v[34:35], s[4:5], v41, s62, v[12:13]
	v_fma_f32 v41, -v40, v43, 1.0
	v_fmac_f32_e32 v43, v41, v43
	v_mul_f32_e32 v41, v42, v43
	v_fma_f32 v50, -v40, v41, v42
	v_fmac_f32_e32 v41, v50, v43
	v_fma_f32 v40, -v40, v41, v42
	v_div_fmas_f32 v40, v40, v43, v41
	v_div_fixup_f32 v20, v40, v20, 1.0
	v_mul_f32_e32 v28, v28, v20
	v_mul_f32_e32 v40, v44, v20
	v_mul_f32_e32 v41, v60, v20
	v_mul_f32_e32 v20, v76, v20
	v_add_u32_e32 v23, s30, v23
	v_add_u32_e32 v25, s30, v25
	v_add_u32_e32 v27, s30, v27
	v_add_u32_e32 v35, s30, v35
	s_waitcnt lgkmcnt(0)
	v_lshlrev_b32_e32 v2, 16, v2
	s_waitcnt lgkmcnt(0)
	v_lshlrev_b32_e32 v36, 16, v36
	s_waitcnt lgkmcnt(0)
	v_lshlrev_b32_e32 v37, 16, v37
	s_waitcnt lgkmcnt(0)
	v_lshlrev_b32_e32 v38, 16, v38
	v_mul_f32_e32 v2, v28, v2
	v_mul_f32_e32 v28, v40, v36
	v_mul_f32_e32 v36, v41, v37
	v_mul_f32_e32 v20, v20, v38
	v_bfe_u32 v37, v2, 16, 1
	v_bfe_u32 v38, v28, 16, 1
	v_bfe_u32 v40, v36, 16, 1
	v_bfe_u32 v41, v20, 16, 1
	v_add3_u32 v2, v2, v37, s61
	v_add3_u32 v28, v28, v38, s61
	v_add3_u32 v36, v36, v40, s61
	v_add3_u32 v20, v20, v41, s61
	ds_write_b16_d16_hi v206, v2 offset:4608
	ds_write_b16_d16_hi v206, v28 offset:4672
	ds_write_b16_d16_hi v206, v36 offset:4736
	ds_write_b16_d16_hi v206, v20 offset:4800
	ds_read_u16 v2, v206 offset:4864
	s_nop 0
	ds_read_u16 v20, v206 offset:4928
	ds_read_u16 v28, v206 offset:4992
	ds_read_u16 v36, v206 offset:5056
	v_div_scale_f32 v38, s[4:5], v21, v21, 1.0
	v_rcp_f32_e32 v41, v38
	v_or_b32_e32 v37, 24, v82
	v_mad_u64_u32 v[18:19], s[4:5], v37, s59, v[8:9]
	v_mad_u64_u32 v[22:23], s[4:5], v39, s62, v[10:11]
	v_add_u32_e32 v19, s2, v19
	v_add_co_u32_e64 v18, s[4:5], s60, v18
	v_div_scale_f32 v40, vcc, 1.0, v21, 1.0
	s_nop 0
	v_addc_co_u32_e64 v19, s[4:5], 0, v19, s[4:5]
	v_mad_u64_u32 v[24:25], s[4:5], v39, s62, v[14:15]
	v_mad_u64_u32 v[26:27], s[4:5], v39, s62, v[16:17]
	v_mad_u64_u32 v[34:35], s[4:5], v39, s62, v[12:13]
	v_fma_f32 v39, -v38, v41, 1.0
	v_fmac_f32_e32 v41, v39, v41
	v_mul_f32_e32 v39, v40, v41
	v_fma_f32 v42, -v38, v39, v40
	v_fmac_f32_e32 v39, v42, v41
	v_fma_f32 v38, -v38, v39, v40
	v_div_fmas_f32 v38, v38, v41, v39
	v_div_fixup_f32 v21, v38, v21, 1.0
	v_mul_f32_e32 v29, v29, v21
	v_mul_f32_e32 v38, v45, v21
	v_mul_f32_e32 v39, v61, v21
	v_mul_f32_e32 v21, v77, v21
	v_add_u32_e32 v23, s30, v23
	v_add_u32_e32 v25, s30, v25
	v_add_u32_e32 v27, s30, v27
	v_add_u32_e32 v35, s30, v35
	s_waitcnt lgkmcnt(0)
; DI float bf2f(unsigned short u) { return __uint_as_float((unsigned)u << 16); }
; DI unsigned f2bf(float f) { unsigned u = __float_as_uint(f); return (u + 0x7fffu + ((u >> 16) & 1u)) >> 16; }
; DI int crow(int i, int hh) { return (i & 3) + 8 * (i >> 2) + 4 * hh; }
; DI void cross_unit(Ctx A_, LAS unsigned char* lds, int kvb, int hc, size_t row0, int nrows, int wave, int lane) {
;     ...
; #pragma unroll
;         for (int nb = 0; nb < 4; ++nb)
; #pragma unroll
;             for (int i = 0; i < 16; ++i) {
;                 const int q = rg * 32 + crow(i, hh);
;                 if (q < nrows) { const size_t eo = (row0 + q) * PLD + hc * 256 + dvh * 128 + nb * 32 + r; Y_[(row0 + q) * YLD + C_YC + hc * 256 + dvh * 128 + nb * 32 + r] = (bf16)f2bf(o[nb][i] * rl[i] * bf2f(P[eo + C_ZC])); }
;             }
	v_lshlrev_b32_e32 v2, 16, v2
	s_waitcnt lgkmcnt(0)
	v_lshlrev_b32_e32 v20, 16, v20
	s_waitcnt lgkmcnt(0)
	v_lshlrev_b32_e32 v28, 16, v28
	s_waitcnt lgkmcnt(0)
	v_lshlrev_b32_e32 v36, 16, v36
	v_mul_f32_e32 v2, v29, v2
	v_mul_f32_e32 v20, v38, v20
	v_mul_f32_e32 v28, v39, v28
	v_mul_f32_e32 v21, v21, v36
	v_bfe_u32 v29, v2, 16, 1
	v_bfe_u32 v36, v20, 16, 1
	v_bfe_u32 v38, v28, 16, 1
	v_bfe_u32 v39, v21, 16, 1
	v_add3_u32 v2, v2, v29, s61
	v_add3_u32 v20, v20, v36, s61
	v_add3_u32 v28, v28, v38, s61
	v_add3_u32 v21, v21, v39, s61
	ds_write_b16_d16_hi v206, v2 offset:4864
	ds_write_b16_d16_hi v206, v20 offset:4928
	ds_write_b16_d16_hi v206, v28 offset:4992
	ds_write_b16_d16_hi v206, v21 offset:5056
	ds_read_u16 v2, v206 offset:6144
	s_nop 0
	ds_read_u16 v28, v206 offset:6208
	ds_read_u16 v29, v206 offset:6272
	ds_read_u16 v34, v206 offset:6336
	s_waitcnt lgkmcnt(0)
	v_div_scale_f32 v36, s[4:5], v4, v4, 1.0
	v_rcp_f32_e32 v39, v36
	v_or_b32_e32 v35, 25, v82
	v_mad_u64_u32 v[18:19], s[4:5], v35, s59, v[8:9]
	v_mad_u64_u32 v[20:21], s[4:5], v37, s62, v[10:11]
	v_add_u32_e32 v19, s2, v19
	v_add_co_u32_e64 v18, s[4:5], s60, v18
	v_div_scale_f32 v38, vcc, 1.0, v4, 1.0
	s_nop 0
	v_addc_co_u32_e64 v19, s[4:5], 0, v19, s[4:5]
	v_mad_u64_u32 v[22:23], s[4:5], v37, s62, v[14:15]
	v_mad_u64_u32 v[24:25], s[4:5], v37, s62, v[16:17]
	v_mad_u64_u32 v[26:27], s[4:5], v37, s62, v[12:13]
	v_fma_f32 v37, -v36, v39, 1.0
	v_fmac_f32_e32 v39, v37, v39
	v_mul_f32_e32 v37, v38, v39
	v_fma_f32 v40, -v36, v37, v38
	v_fmac_f32_e32 v37, v40, v39
	v_fma_f32 v36, -v36, v37, v38
	v_div_fmas_f32 v36, v36, v39, v37
	v_div_fixup_f32 v4, v36, v4, 1.0
	v_mul_f32_e32 v30, v30, v4
	v_mul_f32_e32 v36, v46, v4
	v_mul_f32_e32 v37, v62, v4
	v_mul_f32_e32 v4, v78, v4
	v_add_u32_e32 v21, s30, v21
	v_add_u32_e32 v23, s30, v23
	v_add_u32_e32 v25, s30, v25
	v_add_u32_e32 v27, s30, v27
	s_waitcnt lgkmcnt(0)
	v_lshlrev_b32_e32 v2, 16, v2
	s_waitcnt lgkmcnt(0)
	v_lshlrev_b32_e32 v28, 16, v28
	s_waitcnt lgkmcnt(0)
	v_lshlrev_b32_e32 v29, 16, v29
	s_waitcnt lgkmcnt(0)
	v_lshlrev_b32_e32 v34, 16, v34
	v_mul_f32_e32 v2, v30, v2
	v_mul_f32_e32 v28, v36, v28
	v_mul_f32_e32 v29, v37, v29
	v_mul_f32_e32 v4, v4, v34
	v_bfe_u32 v30, v2, 16, 1
	v_bfe_u32 v34, v28, 16, 1
	v_bfe_u32 v36, v29, 16, 1
	v_bfe_u32 v37, v4, 16, 1
	v_add3_u32 v2, v2, v30, s61
	v_add3_u32 v28, v28, v34, s61
	v_add3_u32 v29, v29, v36, s61
	v_add3_u32 v4, v4, v37, s61
	ds_write_b16_d16_hi v206, v2 offset:6144
	ds_write_b16_d16_hi v206, v28 offset:6208
	ds_write_b16_d16_hi v206, v29 offset:6272
	ds_write_b16_d16_hi v206, v4 offset:6336
	ds_read_u16 v2, v206 offset:6400
	s_nop 0
	ds_read_u16 v4, v206 offset:6464
	ds_read_u16 v28, v206 offset:6528
	ds_read_u16 v29, v206 offset:6592
	v_div_scale_f32 v34, s[4:5], v5, v5, 1.0
	v_rcp_f32_e32 v37, v34
	v_or_b32_e32 v30, 26, v82
	v_mad_u64_u32 v[18:19], s[4:5], v30, s59, v[8:9]
	v_mad_u64_u32 v[20:21], s[4:5], v35, s62, v[10:11]
	v_add_u32_e32 v19, s2, v19
	v_add_co_u32_e64 v18, s[4:5], s60, v18
	v_div_scale_f32 v36, vcc, 1.0, v5, 1.0
	s_nop 0
	v_addc_co_u32_e64 v19, s[4:5], 0, v19, s[4:5]
	v_mad_u64_u32 v[22:23], s[4:5], v35, s62, v[14:15]
	v_mad_u64_u32 v[24:25], s[4:5], v35, s62, v[16:17]
	v_mad_u64_u32 v[26:27], s[4:5], v35, s62, v[12:13]
	v_fma_f32 v35, -v34, v37, 1.0
	v_fmac_f32_e32 v37, v35, v37
	v_mul_f32_e32 v35, v36, v37
	v_fma_f32 v38, -v34, v35, v36
	v_fmac_f32_e32 v35, v38, v37
	v_fma_f32 v34, -v34, v35, v36
	v_div_fmas_f32 v34, v34, v37, v35
	v_div_fixup_f32 v5, v34, v5, 1.0
	v_mul_f32_e32 v31, v31, v5
	v_mul_f32_e32 v34, v47, v5
	v_mul_f32_e32 v35, v63, v5
	v_mul_f32_e32 v5, v79, v5
	v_add_u32_e32 v21, s30, v21
	v_add_u32_e32 v23, s30, v23
	v_add_u32_e32 v25, s30, v25
	v_add_u32_e32 v27, s30, v27
	s_waitcnt lgkmcnt(0)
	v_lshlrev_b32_e32 v2, 16, v2
	s_waitcnt lgkmcnt(0)
	v_lshlrev_b32_e32 v4, 16, v4
	s_waitcnt lgkmcnt(0)
	v_lshlrev_b32_e32 v28, 16, v28
	s_waitcnt lgkmcnt(0)
	v_lshlrev_b32_e32 v29, 16, v29
	v_mul_f32_e32 v2, v31, v2
	v_mul_f32_e32 v4, v34, v4
	v_mul_f32_e32 v28, v35, v28
	v_mul_f32_e32 v5, v5, v29
	v_bfe_u32 v29, v2, 16, 1
	v_bfe_u32 v31, v4, 16, 1
	v_bfe_u32 v34, v28, 16, 1
	v_bfe_u32 v35, v5, 16, 1
	v_add3_u32 v2, v2, v29, s61
	v_add3_u32 v4, v4, v31, s61
	v_add3_u32 v28, v28, v34, s61
	v_add3_u32 v5, v5, v35, s61
	ds_write_b16_d16_hi v206, v2 offset:6400
	ds_write_b16_d16_hi v206, v4 offset:6464
	ds_write_b16_d16_hi v206, v28 offset:6528
	ds_write_b16_d16_hi v206, v5 offset:6592
	ds_read_u16 v2, v206 offset:6656
	s_nop 0
	ds_read_u16 v24, v206 offset:6720
	ds_read_u16 v25, v206 offset:6784
	ds_read_u16 v26, v206 offset:6848
	v_div_scale_f32 v28, s[4:5], v6, v6, 1.0
	v_rcp_f32_e32 v31, v28
	v_or_b32_e32 v27, 27, v82
	v_mad_u64_u32 v[4:5], s[4:5], v27, s59, v[8:9]
	v_mad_u64_u32 v[8:9], s[4:5], v30, s62, v[10:11]
	v_add_u32_e32 v5, s2, v5
	v_add_co_u32_e64 v4, s[4:5], s60, v4
	v_div_scale_f32 v29, vcc, 1.0, v6, 1.0
	s_nop 0
	v_addc_co_u32_e64 v5, s[4:5], 0, v5, s[4:5]
	v_mad_u64_u32 v[18:19], s[4:5], v30, s62, v[14:15]
	v_mad_u64_u32 v[20:21], s[4:5], v30, s62, v[16:17]
	v_mad_u64_u32 v[22:23], s[4:5], v30, s62, v[12:13]
	v_fma_f32 v30, -v28, v31, 1.0
	v_fmac_f32_e32 v31, v30, v31
	v_mul_f32_e32 v30, v29, v31
	v_fma_f32 v34, -v28, v30, v29
	v_fmac_f32_e32 v30, v34, v31
	v_fma_f32 v28, -v28, v30, v29
	v_div_fmas_f32 v28, v28, v31, v30
	v_div_fixup_f32 v6, v28, v6, 1.0
	v_mul_f32_e32 v28, v32, v6
	v_mul_f32_e32 v29, v48, v6
	v_mul_f32_e32 v30, v64, v6
	v_mul_f32_e32 v6, v80, v6
	v_add_u32_e32 v9, s30, v9
	v_add_u32_e32 v19, s30, v19
	v_add_u32_e32 v21, s30, v21
	v_add_u32_e32 v23, s30, v23
	v_mad_u64_u32 v[12:13], s[4:5], v27, s62, v[12:13]
	v_add_u32_e32 v13, s30, v13
	s_waitcnt lgkmcnt(0)
; DI float bf2f(unsigned short u) { return __uint_as_float((unsigned)u << 16); }
; DI unsigned f2bf(float f) { unsigned u = __float_as_uint(f); return (u + 0x7fffu + ((u >> 16) & 1u)) >> 16; }
; DI int crow(int i, int hh) { return (i & 3) + 8 * (i >> 2) + 4 * hh; }
; DI void cross_unit(Ctx A_, LAS unsigned char* lds, int kvb, int hc, size_t row0, int nrows, int wave, int lane) {
;     ...
; #pragma unroll
;         for (int nb = 0; nb < 4; ++nb)
; #pragma unroll
;             for (int i = 0; i < 16; ++i) {
;                 const int q = rg * 32 + crow(i, hh);
;                 if (q < nrows) { const size_t eo = (row0 + q) * PLD + hc * 256 + dvh * 128 + nb * 32 + r; Y_[(row0 + q) * YLD + C_YC + hc * 256 + dvh * 128 + nb * 32 + r] = (bf16)f2bf(o[nb][i] * rl[i] * bf2f(P[eo + C_ZC])); }
;             }
;     }
;     asm volatile("s_waitcnt vmcnt(0) lgkmcnt(0)" ::: "memory"); __builtin_amdgcn_s_barrier(); asm volatile("" ::: "memory");
	v_lshlrev_b32_e32 v2, 16, v2
	s_waitcnt lgkmcnt(0)
	v_lshlrev_b32_e32 v24, 16, v24
	s_waitcnt lgkmcnt(0)
	v_lshlrev_b32_e32 v25, 16, v25
	s_waitcnt lgkmcnt(0)
	v_lshlrev_b32_e32 v26, 16, v26
	v_mul_f32_e32 v2, v28, v2
	v_mul_f32_e32 v24, v29, v24
	v_mul_f32_e32 v25, v30, v25
	v_mul_f32_e32 v6, v6, v26
	v_bfe_u32 v26, v2, 16, 1
	v_bfe_u32 v28, v24, 16, 1
	v_bfe_u32 v29, v25, 16, 1
	v_bfe_u32 v30, v6, 16, 1
	v_add3_u32 v2, v2, v26, s61
	v_add3_u32 v24, v24, v28, s61
	v_add3_u32 v25, v25, v29, s61
	v_add3_u32 v6, v6, v30, s61
	ds_write_b16_d16_hi v206, v2 offset:6656
	ds_write_b16_d16_hi v206, v24 offset:6720
	ds_write_b16_d16_hi v206, v25 offset:6784
	ds_write_b16_d16_hi v206, v6 offset:6848
	ds_read_u16 v2, v206 offset:6912
	s_nop 0
	ds_read_u16 v6, v206 offset:6976
	ds_read_u16 v18, v206 offset:7040
	ds_read_u16 v19, v206 offset:7104
	v_div_scale_f32 v20, s[4:5], v7, v7, 1.0
	v_rcp_f32_e32 v22, v20
	v_mad_u64_u32 v[8:9], s[4:5], v27, s62, v[14:15]
	v_div_scale_f32 v21, vcc, 1.0, v7, 1.0
	v_fma_f32 v14, -v20, v22, 1.0
	v_fmac_f32_e32 v22, v14, v22
	v_mul_f32_e32 v14, v21, v22
	v_fma_f32 v15, -v20, v14, v21
	v_fmac_f32_e32 v14, v15, v22
	v_fma_f32 v15, -v20, v14, v21
	v_div_fmas_f32 v14, v15, v22, v14
	v_div_fixup_f32 v7, v14, v7, 1.0
	v_mul_f32_e32 v14, v33, v7
	v_mad_u64_u32 v[4:5], s[4:5], v27, s62, v[10:11]
	v_mad_u64_u32 v[10:11], s[4:5], v27, s62, v[16:17]
	v_mul_f32_e32 v15, v49, v7
	v_mul_f32_e32 v16, v65, v7
	v_mul_f32_e32 v7, v81, v7
	v_add_u32_e32 v5, s30, v5
	v_add_u32_e32 v9, s30, v9
	v_add_u32_e32 v11, s30, v11
	s_waitcnt lgkmcnt(0)
	v_lshlrev_b32_e32 v2, 16, v2
	s_waitcnt lgkmcnt(0)
	v_lshlrev_b32_e32 v6, 16, v6
	s_waitcnt lgkmcnt(0)
	v_lshlrev_b32_e32 v17, 16, v18
	s_waitcnt lgkmcnt(0)
	v_lshlrev_b32_e32 v18, 16, v19
	v_mul_f32_e32 v2, v14, v2
	v_mul_f32_e32 v6, v15, v6
	v_mul_f32_e32 v14, v16, v17
	v_mul_f32_e32 v7, v7, v18
	v_bfe_u32 v15, v2, 16, 1
	v_bfe_u32 v16, v6, 16, 1
	v_bfe_u32 v17, v14, 16, 1
	v_bfe_u32 v18, v7, 16, 1
	v_add3_u32 v2, v2, v15, s61
	v_add3_u32 v6, v6, v16, s61
	v_add3_u32 v14, v14, v17, s61
	v_add3_u32 v7, v7, v18, s61
	ds_write_b16_d16_hi v206, v2 offset:6912
	ds_write_b16_d16_hi v206, v6 offset:6976
	ds_write_b16_d16_hi v206, v14 offset:7040
	ds_write_b16_d16_hi v206, v7 offset:7104
	s_waitcnt lgkmcnt(0)
	v_and_b32_e32 v207, 63, v0
	v_lshlrev_b32_e32 v208, 4, v207
	v_lshrrev_b32_e32 v210, 4, v207
	v_readfirstlane_b32 s98, v0
	s_lshr_b32 s98, s98, 6
	s_lshl_b32 s98, s98, 13
	s_add_u32 s98, s98, 0x10000
	v_add_u32_e32 v208, s98, v208
	v_mul_u32_u24_e32 v210, 0x1800, v210
	v_and_b32_e32 v207, 15, v207
	v_lshl_or_b32 v210, v207, 4, v210
	ds_read_b128 v[212:215], v208
	ds_read_b128 v[216:219], v208 offset:1024
	ds_read_b128 v[220:223], v208 offset:2048
	ds_read_b128 v[224:227], v208 offset:3072
	ds_read_b128 v[228:231], v208 offset:4096
	ds_read_b128 v[232:235], v208 offset:5120
	ds_read_b128 v[236:239], v208 offset:6144
	ds_read_b128 v[240:243], v208 offset:7168
	s_mul_hi_u32 s99, s101, 0x1800
	s_mul_i32 s98, s101, 0x1800
	v_readlane_b32 vcc_lo, v254, 62
	v_readlane_b32 vcc_hi, v254, 63
	s_add_u32 s98, s98, vcc_lo
	s_addc_u32 s99, s99, vcc_hi
	s_add_u32 s98, s98, 0x64900000
	s_addc_u32 s99, s99, 0
	s_sub_u32 s100, s100, 0x4000
	s_add_u32 s98, s98, s100
	s_addc_u32 s99, s99, 0
	s_waitcnt lgkmcnt(7)
	global_store_dwordx4 v210, v[212:215], s[98:99]
	s_add_u32 s98, s98, 0x6000
	s_addc_u32 s99, s99, 0
	s_waitcnt lgkmcnt(6)
	global_store_dwordx4 v210, v[216:219], s[98:99]
	s_add_u32 s98, s98, 0x6000
	s_addc_u32 s99, s99, 0
	s_waitcnt lgkmcnt(5)
	global_store_dwordx4 v210, v[220:223], s[98:99]
	s_add_u32 s98, s98, 0x6000
	s_addc_u32 s99, s99, 0
	s_waitcnt lgkmcnt(4)
	global_store_dwordx4 v210, v[224:227], s[98:99]
	s_add_u32 s98, s98, 0x6000
	s_addc_u32 s99, s99, 0
	s_waitcnt lgkmcnt(3)
	global_store_dwordx4 v210, v[228:231], s[98:99]
	s_add_u32 s98, s98, 0x6000
	s_addc_u32 s99, s99, 0
	s_waitcnt lgkmcnt(2)
	global_store_dwordx4 v210, v[232:235], s[98:99]
	s_add_u32 s98, s98, 0x6000
	s_addc_u32 s99, s99, 0
	s_waitcnt lgkmcnt(1)
	global_store_dwordx4 v210, v[236:239], s[98:99]
	s_add_u32 s98, s98, 0x6000
	s_addc_u32 s99, s99, 0
	s_waitcnt lgkmcnt(0)
	global_store_dwordx4 v210, v[240:243], s[98:99]
	s_waitcnt lgkmcnt(0)
	s_barrier
